# GU epilogue: 32 adjacent scalar mul/add pairs packed (v_pk_mul_f32 / v_pk_add_f32)
# baseline (speedup 1.0000x reference)
.LBB0_1106:
	s_lshl_b32 s0, s29, 8
	v_mov_b32_e32 v0, v193
	s_add_i32 s0, s0, s77
	v_pk_mul_f32 v[128:129], v[124:125], v[128:129]
	v_bfe_u32 v180, v0, 4, 2
	v_and_or_b32 v160, v0, 15, s0
	v_lshlrev_b32_e32 v0, 4, v180
	v_ashrrev_i32_e32 v161, 31, v160
	v_lshl_add_u64 v[130:131], s[10:11], 0, v[0:1]
	v_lshlrev_b64 v[132:133], 6, v[160:161]
	v_lshl_add_u64 v[132:133], v[130:131], 0, v[132:133]
	v_or_b32_e32 v158, 16, v160
	v_ashrrev_i32_e32 v159, 31, v158
	v_or_b32_e32 v156, 32, v160
	v_ashrrev_i32_e32 v157, 31, v156
	v_or_b32_e32 v154, 48, v160
	v_ashrrev_i32_e32 v155, 31, v154
	v_add_u32_e32 v152, 0x80, v160
	v_ashrrev_i32_e32 v153, 31, v152
	v_add_u32_e32 v150, 0x90, v160
	v_ashrrev_i32_e32 v151, 31, v150
	s_mov_b32 s0, 0x358637bd
	v_pk_mul_f32 v[120:121], v[116:117], v[120:121]
	v_pk_mul_f32 v[112:113], v[108:109], v[112:113]
	v_pk_mul_f32 v[104:105], v[100:101], v[104:105]
	v_pk_mul_f32 v[96:97], v[92:93], v[96:97]
	v_pk_mul_f32 v[88:89], v[84:85], v[88:89]
	v_pk_mul_f32 v[80:81], v[76:77], v[80:81]
	v_pk_mul_f32 v[72:73], v[68:69], v[72:73]
	v_pk_mul_f32 v[64:65], v[60:61], v[64:65]
	v_pk_mul_f32 v[56:57], v[52:53], v[56:57]
	v_pk_mul_f32 v[48:49], v[44:45], v[48:49]
	v_pk_mul_f32 v[40:41], v[36:37], v[40:41]
	v_pk_mul_f32 v[32:33], v[28:29], v[32:33]
	v_pk_mul_f32 v[24:25], v[20:21], v[24:25]
	v_pk_mul_f32 v[16:17], v[12:13], v[16:17]
	v_pk_mul_f32 v[2:3], v[6:7], v[2:3]
	v_pk_mul_f32 v[4:5], v[8:9], v[4:5]
	s_waitcnt lgkmcnt(0)
	v_mov_b32_e32 v0, v221
	ds_swizzle_b32 v132, v0 offset:swizzle(SWAP,16)
	s_waitcnt lgkmcnt(0)
	v_add_f32_e32 v163, v0, v132
	v_mov_b32_e32 v165, v163
	s_nop 1
	v_permlane32_swap_b32_e32 v163, v165
	s_waitcnt lgkmcnt(0)
	v_mov_b32_e32 v0, v222
	ds_swizzle_b32 v132, v0 offset:swizzle(SWAP,16)
	s_waitcnt lgkmcnt(0)
	v_add_f32_e32 v166, v0, v132
	v_mov_b32_e32 v168, v166
	s_nop 1
	v_permlane32_swap_b32_e32 v166, v168
	s_waitcnt lgkmcnt(0)
	v_mov_b32_e32 v0, v223
	ds_swizzle_b32 v132, v0 offset:swizzle(SWAP,16)
	s_waitcnt lgkmcnt(0)
	v_add_f32_e32 v167, v0, v132
	v_mov_b32_e32 v169, v167
	s_nop 1
	v_permlane32_swap_b32_e32 v167, v169
	v_pk_add_f32 v[166:167], v[166:167], v[168:169]
	s_waitcnt lgkmcnt(0)
	v_mov_b32_e32 v0, v224
	ds_swizzle_b32 v132, v0 offset:swizzle(SWAP,16)
	s_waitcnt lgkmcnt(0)
	v_add_f32_e32 v170, v0, v132
	v_mov_b32_e32 v172, v170
	s_nop 1
	v_permlane32_swap_b32_e32 v170, v172
	s_waitcnt lgkmcnt(0)
	v_mov_b32_e32 v132, v195
	v_mov_b32_e32 v133, v196
	v_mov_b32_e32 v195, v197
	v_pk_add_f32 v[132:133], v[132:133], v[194:195]
	s_nop 0
	v_add_f32_e32 v0, v132, v133
	ds_swizzle_b32 v132, v0 offset:swizzle(SWAP,16)
	s_waitcnt lgkmcnt(0)
	v_add_f32_e32 v171, v0, v132
	v_mov_b32_e32 v173, v171
	s_nop 1
	v_permlane32_swap_b32_e32 v171, v173
	v_pk_add_f32 v[170:171], v[170:171], v[172:173]
	s_waitcnt lgkmcnt(0)
	v_mov_b32_e32 v132, v199
	v_mov_b32_e32 v133, v200
	v_mov_b32_e32 v199, v201
	v_pk_add_f32 v[132:133], v[132:133], v[198:199]
	v_add_u32_e32 v148, 0xa0, v160
	v_add_f32_e32 v0, v132, v133
	ds_swizzle_b32 v132, v0 offset:swizzle(SWAP,16)
	v_ashrrev_i32_e32 v149, 31, v148
	v_add_u32_e32 v146, 0xb0, v160
	v_ashrrev_i32_e32 v147, 31, v146
	s_waitcnt lgkmcnt(0)
	v_add_f32_e32 v174, v0, v132
	v_mov_b32_e32 v176, v174
	s_nop 1
	v_permlane32_swap_b32_e32 v174, v176
	s_waitcnt lgkmcnt(0)
	v_mov_b32_e32 v132, v203
	v_mov_b32_e32 v133, v204
	v_mov_b32_e32 v203, v205
	v_pk_add_f32 v[132:133], v[132:133], v[202:203]
	s_nop 0
	v_add_f32_e32 v0, v132, v133
	ds_swizzle_b32 v132, v0 offset:swizzle(SWAP,16)
	s_waitcnt lgkmcnt(0)
	v_add_f32_e32 v175, v0, v132
	v_mov_b32_e32 v177, v175
	s_nop 1
	v_permlane32_swap_b32_e32 v175, v177
	v_pk_add_f32 v[174:175], v[174:175], v[176:177]
	v_mov_b64_e32 v[176:177], s[0:1]
	v_pk_fma_f32 v[174:175], v[174:175], s[62:63], v[176:177] op_sel_hi:[1,0,0]
	v_pk_fma_f32 v[170:171], v[170:171], s[62:63], v[176:177] op_sel_hi:[1,0,0]
	v_mul_f32_e32 v0, 0x4b800000, v175
	v_cmp_gt_f32_e64 s[2:3], s60, v175
	v_cmp_gt_f32_e32 vcc, s60, v174
	v_pk_fma_f32 v[166:167], v[166:167], s[62:63], v[176:177] op_sel_hi:[1,0,0]
	v_cndmask_b32_e64 v0, v175, v0, s[2:3]
	v_rsq_f32_e32 v0, v0
	s_lshl_b32 s0, s28, 7
	v_mul_f32_e32 v147, 0x45800000, v0
	v_cndmask_b32_e64 v147, v0, v147, s[2:3]
	v_mul_f32_e32 v0, 0x4b800000, v174
	v_cndmask_b32_e32 v0, v174, v0, vcc
	v_rsq_f32_e32 v0, v0
	v_cmp_gt_f32_e64 s[2:3], s60, v171
	v_mul_f32_e32 v149, 0x45800000, v0
	v_cndmask_b32_e32 v149, v0, v149, vcc
	v_mul_f32_e32 v0, 0x4b800000, v171
	v_cndmask_b32_e64 v0, v171, v0, s[2:3]
	v_rsq_f32_e32 v0, v0
	v_cmp_gt_f32_e32 vcc, s60, v170
	v_mul_f32_e32 v151, 0x45800000, v0
	v_cndmask_b32_e64 v151, v0, v151, s[2:3]
	v_mul_f32_e32 v0, 0x4b800000, v170
	v_cndmask_b32_e32 v0, v170, v0, vcc
	v_rsq_f32_e32 v0, v0
	v_cmp_gt_f32_e64 s[2:3], s60, v167
	v_mul_f32_e32 v153, 0x45800000, v0
	v_cndmask_b32_e32 v153, v0, v153, vcc
	v_mul_f32_e32 v0, 0x4b800000, v167
	v_cndmask_b32_e64 v0, v167, v0, s[2:3]
	v_rsq_f32_e32 v0, v0
	v_cmp_gt_f32_e32 vcc, s60, v166
	v_mul_f32_e32 v155, 0x45800000, v0
	v_cndmask_b32_e64 v155, v0, v155, s[2:3]
	v_mul_f32_e32 v0, 0x4b800000, v166
	v_cndmask_b32_e32 v0, v166, v0, vcc
	v_rsq_f32_e32 v0, v0
	s_waitcnt lgkmcnt(0)
	v_mov_b32_e32 v166, v207
	v_mov_b32_e32 v167, v208
	v_mov_b32_e32 v207, v209
	v_mul_f32_e32 v157, 0x45800000, v0
	v_pk_add_f32 v[130:131], v[166:167], v[206:207]
	v_cndmask_b32_e32 v157, v0, v157, vcc
	v_add_f32_e32 v0, v130, v131
	ds_swizzle_b32 v130, v0 offset:swizzle(SWAP,16)
	s_waitcnt lgkmcnt(0)
	v_add_f32_e32 v162, v0, v130
	v_mov_b32_e32 v164, v162
	s_nop 1
	v_permlane32_swap_b32_e32 v162, v164
	v_pk_add_f32 v[130:131], v[162:163], v[164:165]
	s_nop 0
	v_pk_fma_f32 v[130:131], v[130:131], s[62:63], v[176:177] op_sel_hi:[1,0,0]
	s_nop 0
	v_mul_f32_e32 v0, 0x4b800000, v131
	v_cmp_gt_f32_e64 s[2:3], s60, v131
	v_cmp_gt_f32_e32 vcc, s60, v130
	s_nop 0
	v_cndmask_b32_e64 v0, v131, v0, s[2:3]
	v_rsq_f32_e32 v0, v0
	s_nop 0
	v_mul_f32_e32 v131, 0x45800000, v0
	v_cndmask_b32_e64 v159, v0, v131, s[2:3]
	v_mul_f32_e32 v163, 0xbfb8aa3b, v159
	v_mul_f32_e32 v162, v159, v159
	v_mul_f32_e32 v159, v122, v163
	v_exp_f32_e32 v159, v159
	v_mul_f32_e32 v0, 0x4b800000, v130
	v_cndmask_b32_e32 v0, v130, v0, vcc
	v_rsq_f32_e32 v0, v0
	v_add_f32_e32 v159, 1.0, v159
	v_rcp_f32_e32 v164, v159
	v_mul_f32_e32 v159, v123, v163
	v_exp_f32_e32 v159, v159
	v_pk_mul_f32 v[122:123], v[122:123], v[126:127]
	v_mul_f32_e32 v130, 0x45800000, v0
	v_cndmask_b32_e32 v0, v0, v130, vcc
	v_add_f32_e32 v159, 1.0, v159
	v_rcp_f32_e32 v165, v159
	v_lshl_or_b32 v130, v180, 3, s0
	v_or_b32_e32 v132, s78, v130
	v_ashrrev_i32_e32 v133, 31, v132
	v_pk_mul_f32 v[126:127], v[162:163], v[164:165] op_sel_hi:[0,1]
	v_pk_mul_f32 v[122:123], v[122:123], v[126:127]
	v_mov_b64_e32 v[130:131], s[8:9]
	v_cvt_pk_bf16_f32 v122, v122, v123
	v_mul_f32_e32 v123, v124, v163
	v_exp_f32_e32 v123, v123
	v_mad_i64_i32 v[160:161], s[2:3], v160, s70, v[130:131]
	v_lshlrev_b64 v[132:133], 1, v[132:133]
	v_add_f32_e32 v123, 1.0, v123
	v_rcp_f32_e32 v124, v123
	v_mul_f32_e32 v123, v125, v163
	v_exp_f32_e32 v123, v123
	v_lshl_add_u64 v[160:161], v[160:161], 0, v[132:133]
	s_andn2_b64 vcc, exec, s[38:39]
	v_add_f32_e32 v123, 1.0, v123
	v_rcp_f32_e32 v125, v123
	s_nop 0
	v_pk_mul_f32 v[124:125], v[162:163], v[124:125] op_sel_hi:[0,1]
	v_pk_mul_f32 v[124:125], v[128:129], v[124:125]
	s_nop 0
	v_cvt_pk_bf16_f32 v123, v124, v125
	v_pk_mul_f32 v[124:125], v[114:115], v[162:163] op_sel:[0,1] op_sel_hi:[1,1]
	v_exp_f32_e32 v124, v124
	v_exp_f32_e32 v125, v125
	v_pk_mul_f32 v[114:115], v[114:115], v[118:119]
	v_pk_add_f32 v[124:125], v[124:125], 1.0 op_sel_hi:[1,0]
	v_rcp_f32_e32 v124, v124
	v_rcp_f32_e32 v125, v125
	s_nop 0
	v_pk_mul_f32 v[118:119], v[162:163], v[124:125] op_sel_hi:[0,1]
	v_pk_mul_f32 v[114:115], v[114:115], v[118:119]
	s_nop 0
	v_cvt_pk_bf16_f32 v124, v114, v115
	v_mul_f32_e32 v115, v117, v163
	v_mul_f32_e32 v117, 0xbfb8aa3b, v157
	v_pk_mul_f32 v[118:119], v[106:107], v[116:117] op_sel:[0,1] op_sel_hi:[1,1]
	v_exp_f32_e32 v118, v118
	v_exp_f32_e32 v119, v119
	v_mul_f32_e32 v114, v116, v163
	v_mul_f32_e32 v116, v157, v157
	v_pk_add_f32 v[118:119], v[118:119], 1.0 op_sel_hi:[1,0]
	v_rcp_f32_e32 v118, v118
	v_rcp_f32_e32 v119, v119
	v_pk_mul_f32 v[106:107], v[106:107], v[110:111]
	v_exp_f32_e32 v114, v114
	v_exp_f32_e32 v115, v115
	v_pk_mul_f32 v[110:111], v[116:117], v[118:119] op_sel_hi:[0,1]
	v_pk_mul_f32 v[106:107], v[106:107], v[110:111]
	v_add_f32_e32 v114, 1.0, v114
	v_cvt_pk_bf16_f32 v106, v106, v107
	v_mul_f32_e32 v107, v108, v117
	v_exp_f32_e32 v107, v107
	v_add_f32_e32 v115, 1.0, v115
	v_rcp_f32_e32 v114, v114
	v_rcp_f32_e32 v115, v115
	v_add_f32_e32 v107, 1.0, v107
	v_rcp_f32_e32 v108, v107
	v_mul_f32_e32 v107, v109, v117
	v_exp_f32_e32 v107, v107
	v_pk_mul_f32 v[114:115], v[162:163], v[114:115] op_sel_hi:[0,1]
	v_pk_mul_f32 v[114:115], v[120:121], v[114:115]
	v_add_f32_e32 v107, 1.0, v107
	v_rcp_f32_e32 v109, v107
	v_cvt_pk_bf16_f32 v125, v114, v115
	v_mad_i64_i32 v[114:115], s[2:3], v158, s70, v[130:131]
	v_pk_mul_f32 v[108:109], v[116:117], v[108:109] op_sel_hi:[0,1]
	v_pk_mul_f32 v[108:109], v[112:113], v[108:109]
	v_lshl_add_u64 v[114:115], v[114:115], 0, v[132:133]
	v_cvt_pk_bf16_f32 v107, v108, v109
	v_pk_mul_f32 v[108:109], v[98:99], v[116:117] op_sel:[0,1] op_sel_hi:[1,1]
	v_exp_f32_e32 v108, v108
	v_exp_f32_e32 v109, v109
	v_pk_mul_f32 v[98:99], v[98:99], v[102:103]
	flat_store_dwordx4 v[160:161], v[122:125]
	v_pk_add_f32 v[108:109], v[108:109], 1.0 op_sel_hi:[1,0]
	v_rcp_f32_e32 v108, v108
	v_rcp_f32_e32 v109, v109
	s_nop 0
	v_pk_mul_f32 v[102:103], v[116:117], v[108:109] op_sel_hi:[0,1]
	v_pk_mul_f32 v[98:99], v[98:99], v[102:103]
	s_nop 0
	v_cvt_pk_bf16_f32 v108, v98, v99
	v_mul_f32_e32 v99, v101, v117
	v_mul_f32_e32 v101, 0xbfb8aa3b, v155
	v_pk_mul_f32 v[102:103], v[90:91], v[100:101] op_sel:[0,1] op_sel_hi:[1,1]
	v_exp_f32_e32 v102, v102
	v_exp_f32_e32 v103, v103
	v_mul_f32_e32 v98, v100, v117
	v_mul_f32_e32 v100, v155, v155
	v_pk_add_f32 v[102:103], v[102:103], 1.0 op_sel_hi:[1,0]
	v_rcp_f32_e32 v102, v102
	v_rcp_f32_e32 v103, v103
	v_pk_mul_f32 v[90:91], v[90:91], v[94:95]
	v_exp_f32_e32 v98, v98
	v_exp_f32_e32 v99, v99
	v_pk_mul_f32 v[94:95], v[100:101], v[102:103] op_sel_hi:[0,1]
	v_pk_mul_f32 v[90:91], v[90:91], v[94:95]
	v_add_f32_e32 v98, 1.0, v98
	v_cvt_pk_bf16_f32 v90, v90, v91
	v_mul_f32_e32 v91, v92, v101
	v_exp_f32_e32 v91, v91
	v_add_f32_e32 v99, 1.0, v99
	v_rcp_f32_e32 v98, v98
	v_rcp_f32_e32 v99, v99
	v_add_f32_e32 v91, 1.0, v91
	v_rcp_f32_e32 v92, v91
	v_mul_f32_e32 v91, v93, v101
	v_exp_f32_e32 v91, v91
	v_pk_mul_f32 v[98:99], v[116:117], v[98:99] op_sel_hi:[0,1]
	v_pk_mul_f32 v[98:99], v[104:105], v[98:99]
	v_add_f32_e32 v91, 1.0, v91
	v_rcp_f32_e32 v93, v91
	v_cvt_pk_bf16_f32 v109, v98, v99
	v_mad_i64_i32 v[98:99], s[2:3], v156, s70, v[130:131]
	v_pk_mul_f32 v[92:93], v[100:101], v[92:93] op_sel_hi:[0,1]
	v_pk_mul_f32 v[92:93], v[96:97], v[92:93]
	v_lshl_add_u64 v[98:99], v[98:99], 0, v[132:133]
	v_cvt_pk_bf16_f32 v91, v92, v93
	v_pk_mul_f32 v[92:93], v[82:83], v[100:101] op_sel:[0,1] op_sel_hi:[1,1]
	v_exp_f32_e32 v92, v92
	v_exp_f32_e32 v93, v93
	v_pk_mul_f32 v[82:83], v[82:83], v[86:87]
	flat_store_dwordx4 v[114:115], v[106:109]
	v_pk_add_f32 v[92:93], v[92:93], 1.0 op_sel_hi:[1,0]
	v_rcp_f32_e32 v92, v92
	v_rcp_f32_e32 v93, v93
	s_nop 0
	v_pk_mul_f32 v[86:87], v[100:101], v[92:93] op_sel_hi:[0,1]
	v_pk_mul_f32 v[82:83], v[82:83], v[86:87]
	s_nop 0
	v_cvt_pk_bf16_f32 v92, v82, v83
	v_mul_f32_e32 v83, v85, v101
	v_mul_f32_e32 v85, 0xbfb8aa3b, v153
	v_pk_mul_f32 v[86:87], v[74:75], v[84:85] op_sel:[0,1] op_sel_hi:[1,1]
	v_exp_f32_e32 v86, v86
	v_exp_f32_e32 v87, v87
	v_mul_f32_e32 v82, v84, v101
	v_mul_f32_e32 v84, v153, v153
	v_pk_add_f32 v[86:87], v[86:87], 1.0 op_sel_hi:[1,0]
	v_rcp_f32_e32 v86, v86
	v_rcp_f32_e32 v87, v87
	v_pk_mul_f32 v[74:75], v[74:75], v[78:79]
	v_exp_f32_e32 v82, v82
	v_exp_f32_e32 v83, v83
	v_pk_mul_f32 v[78:79], v[84:85], v[86:87] op_sel_hi:[0,1]
	v_pk_mul_f32 v[74:75], v[74:75], v[78:79]
	v_add_f32_e32 v82, 1.0, v82
	v_cvt_pk_bf16_f32 v74, v74, v75
	v_mul_f32_e32 v75, v76, v85
	v_exp_f32_e32 v75, v75
	v_add_f32_e32 v83, 1.0, v83
	v_rcp_f32_e32 v82, v82
	v_rcp_f32_e32 v83, v83
	v_add_f32_e32 v75, 1.0, v75
	v_rcp_f32_e32 v76, v75
	v_mul_f32_e32 v75, v77, v85
	v_exp_f32_e32 v75, v75
	v_pk_mul_f32 v[82:83], v[100:101], v[82:83] op_sel_hi:[0,1]
	v_pk_mul_f32 v[82:83], v[88:89], v[82:83]
	v_add_f32_e32 v75, 1.0, v75
	v_rcp_f32_e32 v77, v75
	v_cvt_pk_bf16_f32 v93, v82, v83
	v_mad_i64_i32 v[82:83], s[2:3], v154, s70, v[130:131]
	v_pk_mul_f32 v[76:77], v[84:85], v[76:77] op_sel_hi:[0,1]
	v_pk_mul_f32 v[76:77], v[80:81], v[76:77]
	v_lshl_add_u64 v[82:83], v[82:83], 0, v[132:133]
	v_cvt_pk_bf16_f32 v75, v76, v77
	v_pk_mul_f32 v[76:77], v[66:67], v[84:85] op_sel:[0,1] op_sel_hi:[1,1]
	v_exp_f32_e32 v76, v76
	v_exp_f32_e32 v77, v77
	v_pk_mul_f32 v[66:67], v[66:67], v[70:71]
	flat_store_dwordx4 v[98:99], v[90:93]
	v_pk_add_f32 v[76:77], v[76:77], 1.0 op_sel_hi:[1,0]
	v_rcp_f32_e32 v76, v76
	v_rcp_f32_e32 v77, v77
	s_nop 0
	v_pk_mul_f32 v[70:71], v[84:85], v[76:77] op_sel_hi:[0,1]
	v_pk_mul_f32 v[66:67], v[66:67], v[70:71]
	s_nop 0
	v_cvt_pk_bf16_f32 v76, v66, v67
	v_mul_f32_e32 v67, v69, v85
	v_mul_f32_e32 v69, 0xbfb8aa3b, v151
	v_pk_mul_f32 v[70:71], v[58:59], v[68:69] op_sel:[0,1] op_sel_hi:[1,1]
	v_exp_f32_e32 v70, v70
	v_exp_f32_e32 v71, v71
	v_mul_f32_e32 v66, v68, v85
	v_mul_f32_e32 v68, v151, v151
	v_pk_add_f32 v[70:71], v[70:71], 1.0 op_sel_hi:[1,0]
	v_rcp_f32_e32 v70, v70
	v_rcp_f32_e32 v71, v71
	v_pk_mul_f32 v[58:59], v[58:59], v[62:63]
	v_exp_f32_e32 v66, v66
	v_exp_f32_e32 v67, v67
	v_pk_mul_f32 v[62:63], v[68:69], v[70:71] op_sel_hi:[0,1]
	v_pk_mul_f32 v[58:59], v[58:59], v[62:63]
	v_add_f32_e32 v66, 1.0, v66
	v_cvt_pk_bf16_f32 v58, v58, v59
	v_mul_f32_e32 v59, v60, v69
	v_exp_f32_e32 v59, v59
	v_add_f32_e32 v67, 1.0, v67
	v_rcp_f32_e32 v66, v66
	v_rcp_f32_e32 v67, v67
	v_add_f32_e32 v59, 1.0, v59
	v_rcp_f32_e32 v60, v59
	v_mul_f32_e32 v59, v61, v69
	v_exp_f32_e32 v59, v59
	v_pk_mul_f32 v[66:67], v[84:85], v[66:67] op_sel_hi:[0,1]
	v_pk_mul_f32 v[66:67], v[72:73], v[66:67]
	v_add_f32_e32 v59, 1.0, v59
	v_rcp_f32_e32 v61, v59
	v_cvt_pk_bf16_f32 v77, v66, v67
	v_mad_i64_i32 v[66:67], s[2:3], v152, s70, v[130:131]
	v_pk_mul_f32 v[60:61], v[68:69], v[60:61] op_sel_hi:[0,1]
	v_pk_mul_f32 v[60:61], v[64:65], v[60:61]
	v_lshl_add_u64 v[66:67], v[66:67], 0, v[132:133]
	v_cvt_pk_bf16_f32 v59, v60, v61
	v_pk_mul_f32 v[60:61], v[50:51], v[68:69] op_sel:[0,1] op_sel_hi:[1,1]
	v_exp_f32_e32 v60, v60
	v_exp_f32_e32 v61, v61
	v_pk_mul_f32 v[50:51], v[50:51], v[54:55]
	flat_store_dwordx4 v[82:83], v[74:77]
	v_pk_add_f32 v[60:61], v[60:61], 1.0 op_sel_hi:[1,0]
	v_rcp_f32_e32 v60, v60
	v_rcp_f32_e32 v61, v61
	s_nop 0
	v_pk_mul_f32 v[54:55], v[68:69], v[60:61] op_sel_hi:[0,1]
	v_pk_mul_f32 v[50:51], v[50:51], v[54:55]
	s_nop 0
	v_cvt_pk_bf16_f32 v60, v50, v51
	v_mul_f32_e32 v51, v53, v69
	v_mul_f32_e32 v53, 0xbfb8aa3b, v149
	v_pk_mul_f32 v[54:55], v[42:43], v[52:53] op_sel:[0,1] op_sel_hi:[1,1]
	v_exp_f32_e32 v54, v54
	v_exp_f32_e32 v55, v55
	v_mul_f32_e32 v50, v52, v69
	v_mul_f32_e32 v52, v149, v149
	v_pk_add_f32 v[54:55], v[54:55], 1.0 op_sel_hi:[1,0]
	v_rcp_f32_e32 v54, v54
	v_rcp_f32_e32 v55, v55
	v_pk_mul_f32 v[42:43], v[42:43], v[46:47]
	v_exp_f32_e32 v50, v50
	v_exp_f32_e32 v51, v51
	v_pk_mul_f32 v[46:47], v[52:53], v[54:55] op_sel_hi:[0,1]
	v_pk_mul_f32 v[42:43], v[42:43], v[46:47]
	v_add_f32_e32 v50, 1.0, v50
	v_cvt_pk_bf16_f32 v42, v42, v43
	v_mul_f32_e32 v43, v44, v53
	v_exp_f32_e32 v43, v43
	v_add_f32_e32 v51, 1.0, v51
	v_rcp_f32_e32 v50, v50
	v_rcp_f32_e32 v51, v51
	v_add_f32_e32 v43, 1.0, v43
	v_rcp_f32_e32 v44, v43
	v_mul_f32_e32 v43, v45, v53
	v_exp_f32_e32 v43, v43
	v_pk_mul_f32 v[50:51], v[68:69], v[50:51] op_sel_hi:[0,1]
	v_pk_mul_f32 v[50:51], v[56:57], v[50:51]
	v_add_f32_e32 v43, 1.0, v43
	v_rcp_f32_e32 v45, v43
	v_cvt_pk_bf16_f32 v61, v50, v51
	v_mad_i64_i32 v[50:51], s[2:3], v150, s70, v[130:131]
	v_pk_mul_f32 v[44:45], v[52:53], v[44:45] op_sel_hi:[0,1]
	v_pk_mul_f32 v[44:45], v[48:49], v[44:45]
	v_lshl_add_u64 v[50:51], v[50:51], 0, v[132:133]
	v_cvt_pk_bf16_f32 v43, v44, v45
	v_pk_mul_f32 v[44:45], v[34:35], v[52:53] op_sel:[0,1] op_sel_hi:[1,1]
	v_exp_f32_e32 v44, v44
	v_exp_f32_e32 v45, v45
	v_pk_mul_f32 v[34:35], v[34:35], v[38:39]
	flat_store_dwordx4 v[66:67], v[58:61]
	v_pk_add_f32 v[44:45], v[44:45], 1.0 op_sel_hi:[1,0]
	v_rcp_f32_e32 v44, v44
	v_rcp_f32_e32 v45, v45
	s_nop 0
	v_pk_mul_f32 v[38:39], v[52:53], v[44:45] op_sel_hi:[0,1]
	v_pk_mul_f32 v[34:35], v[34:35], v[38:39]
	s_nop 0
	v_cvt_pk_bf16_f32 v44, v34, v35
	v_mul_f32_e32 v35, v37, v53
	v_mul_f32_e32 v37, 0xbfb8aa3b, v147
	v_pk_mul_f32 v[38:39], v[26:27], v[36:37] op_sel:[0,1] op_sel_hi:[1,1]
	v_exp_f32_e32 v38, v38
	v_exp_f32_e32 v39, v39
	v_mul_f32_e32 v34, v36, v53
	v_mul_f32_e32 v36, v147, v147
	v_pk_add_f32 v[38:39], v[38:39], 1.0 op_sel_hi:[1,0]
	v_rcp_f32_e32 v38, v38
	v_rcp_f32_e32 v39, v39
	v_pk_mul_f32 v[26:27], v[26:27], v[30:31]
	v_exp_f32_e32 v34, v34
	v_exp_f32_e32 v35, v35
	v_pk_mul_f32 v[30:31], v[36:37], v[38:39] op_sel_hi:[0,1]
	v_pk_mul_f32 v[26:27], v[26:27], v[30:31]
	v_add_f32_e32 v34, 1.0, v34
	v_cvt_pk_bf16_f32 v26, v26, v27
	v_mul_f32_e32 v27, v28, v37
	v_exp_f32_e32 v27, v27
	v_add_f32_e32 v35, 1.0, v35
	v_rcp_f32_e32 v34, v34
	v_rcp_f32_e32 v35, v35
	v_add_f32_e32 v27, 1.0, v27
	v_rcp_f32_e32 v28, v27
	v_mul_f32_e32 v27, v29, v37
	v_exp_f32_e32 v27, v27
	v_pk_mul_f32 v[34:35], v[52:53], v[34:35] op_sel_hi:[0,1]
	v_pk_mul_f32 v[34:35], v[40:41], v[34:35]
	v_add_f32_e32 v27, 1.0, v27
	v_rcp_f32_e32 v29, v27
	v_cvt_pk_bf16_f32 v45, v34, v35
	v_mad_i64_i32 v[34:35], s[2:3], v148, s70, v[130:131]
	v_pk_mul_f32 v[28:29], v[36:37], v[28:29] op_sel_hi:[0,1]
	v_pk_mul_f32 v[28:29], v[32:33], v[28:29]
	v_lshl_add_u64 v[34:35], v[34:35], 0, v[132:133]
	v_cvt_pk_bf16_f32 v27, v28, v29
	v_pk_mul_f32 v[28:29], v[18:19], v[36:37] op_sel:[0,1] op_sel_hi:[1,1]
	v_exp_f32_e32 v28, v28
	v_exp_f32_e32 v29, v29
	v_pk_mul_f32 v[18:19], v[18:19], v[22:23]
	flat_store_dwordx4 v[50:51], v[42:45]
	v_pk_add_f32 v[28:29], v[28:29], 1.0 op_sel_hi:[1,0]
	v_rcp_f32_e32 v28, v28
	v_rcp_f32_e32 v29, v29
	s_nop 0
	v_pk_mul_f32 v[22:23], v[36:37], v[28:29] op_sel_hi:[0,1]
	v_pk_mul_f32 v[18:19], v[18:19], v[22:23]
	v_mul_f32_e32 v22, 0xbfb8aa3b, v0
	v_cvt_pk_bf16_f32 v28, v18, v19
	v_pk_mul_f32 v[18:19], v[20:21], v[36:37] op_sel:[0,1] op_sel_hi:[1,1]
	v_pk_mul_f32 v[20:21], v[10:11], v[22:23] op_sel_hi:[1,0]
	v_exp_f32_e32 v20, v20
	v_exp_f32_e32 v21, v21
	v_mul_f32_e32 v0, v0, v0
	v_pk_mul_f32 v[10:11], v[10:11], v[14:15]
	v_pk_add_f32 v[20:21], v[20:21], 1.0 op_sel_hi:[1,0]
	v_rcp_f32_e32 v20, v20
	v_rcp_f32_e32 v21, v21
	v_exp_f32_e32 v18, v18
	v_exp_f32_e32 v19, v19
	v_pk_mul_f32 v[14:15], v[0:1], v[20:21] op_sel_hi:[0,1]
	v_pk_mul_f32 v[10:11], v[10:11], v[14:15]
	v_add_f32_e32 v18, 1.0, v18
	v_cvt_pk_bf16_f32 v10, v10, v11
	v_mul_f32_e32 v11, v12, v22
	v_exp_f32_e32 v11, v11
	v_add_f32_e32 v19, 1.0, v19
	v_rcp_f32_e32 v18, v18
	v_rcp_f32_e32 v19, v19
	v_add_f32_e32 v11, 1.0, v11
	v_rcp_f32_e32 v12, v11
	v_mul_f32_e32 v11, v13, v22
	v_exp_f32_e32 v11, v11
	v_pk_mul_f32 v[18:19], v[36:37], v[18:19] op_sel_hi:[0,1]
	v_pk_mul_f32 v[18:19], v[24:25], v[18:19]
	v_add_f32_e32 v11, 1.0, v11
	v_rcp_f32_e32 v13, v11
	v_cvt_pk_bf16_f32 v29, v18, v19
	v_mad_i64_i32 v[18:19], s[2:3], v146, s70, v[130:131]
	v_pk_mul_f32 v[12:13], v[0:1], v[12:13] op_sel_hi:[0,1]
	v_pk_mul_f32 v[12:13], v[16:17], v[12:13]
	v_lshl_add_u64 v[18:19], v[18:19], 0, v[132:133]
	v_cvt_pk_bf16_f32 v11, v12, v13
	v_pk_mul_f32 v[12:13], v[6:7], v[22:23] op_sel_hi:[1,0]
	v_exp_f32_e32 v12, v12
	v_exp_f32_e32 v13, v13
	s_mov_b64 s[2:3], -1
	flat_store_dwordx4 v[34:35], v[26:29]
	v_pk_add_f32 v[12:13], v[12:13], 1.0 op_sel_hi:[1,0]
	v_rcp_f32_e32 v12, v12
	v_rcp_f32_e32 v13, v13
	s_nop 0
	v_pk_mul_f32 v[6:7], v[0:1], v[12:13] op_sel_hi:[0,1]
	v_pk_mul_f32 v[2:3], v[2:3], v[6:7]
	s_nop 0
	v_cvt_pk_bf16_f32 v12, v2, v3
	v_pk_mul_f32 v[2:3], v[8:9], v[22:23] op_sel_hi:[1,0]
	v_exp_f32_e32 v2, v2
	v_exp_f32_e32 v3, v3
	v_add_f32_e32 v2, 1.0, v2
	v_add_f32_e32 v3, 1.0, v3
	v_rcp_f32_e32 v2, v2
	v_rcp_f32_e32 v3, v3
	s_nop 0
	v_pk_mul_f32 v[2:3], v[0:1], v[2:3] op_sel_hi:[0,1]
	v_pk_mul_f32 v[2:3], v[4:5], v[2:3]
	s_nop 0
	v_cvt_pk_bf16_f32 v13, v2, v3
	flat_store_dwordx4 v[18:19], v[10:13]
	s_cbranch_vccnz .LBB0_1099
	s_andn2_b64 vcc, exec, s[6:7]
	s_cbranch_vccnz .LBB0_1098
	s_barrier
	s_branch .LBB0_1098
